# branch-GEMM epilogue: gate/partial-sum loads batched 8 blocks at a time with one counted wait per block instead of a vmcnt(0) round trip per block
# speedup vs baseline: 1.0042x; 1.0042x over previous
.LBB0_192:
	v_lshl_add_u32 v134, s16, 8, v64
	v_lshl_or_b32 v132, s64, 8, v143
	v_lshlrev_b32_e32 v134, 12, v134
	v_lshl_add_u32 v132, v132, 1, v134
	v_readfirstlane_b32 s64, v130
	v_readfirstlane_b32 s65, v131
	s_nop 4
	v_mov_b32_e32 v133, v132
	global_load_dwordx4 v[196:199], v133, s[4:5]
	global_load_dwordx4 v[200:203], v133, s[4:5] offset:256
	v_add_u32_e32 v133, 0x10000, v132
	global_load_dwordx4 v[204:207], v133, s[4:5]
	global_load_dwordx4 v[208:211], v133, s[4:5] offset:256
	v_add_u32_e32 v133, 0x20000, v132
	global_load_dwordx4 v[212:215], v133, s[4:5]
	global_load_dwordx4 v[216:219], v133, s[4:5] offset:256
	v_add_u32_e32 v133, 0x30000, v132
	global_load_dwordx4 v[220:223], v133, s[4:5]
	global_load_dwordx4 v[224:227], v133, s[4:5] offset:256
	s_cmp_lg_u64 s[12:13], 0
	s_cbranch_scc0 .Lepb_nom0
	v_mov_b32_e32 v133, v132
	global_load_dwordx4 v[228:231], v133, s[64:65]
	global_load_dwordx4 v[232:235], v133, s[64:65] offset:256
	v_add_u32_e32 v133, 0x10000, v132
	global_load_dwordx4 v[236:239], v133, s[64:65]
	global_load_dwordx4 v[240:243], v133, s[64:65] offset:256
	v_add_u32_e32 v133, 0x20000, v132
	global_load_dwordx4 v[244:247], v133, s[64:65]
	global_load_dwordx4 v[176:179], v133, s[64:65] offset:256
	v_add_u32_e32 v133, 0x30000, v132
	global_load_dwordx4 v[134:137], v133, s[64:65]
	global_load_dwordx4 v[138:141], v133, s[64:65] offset:256
.Lepb_nom0:
	s_waitcnt vmcnt(7)
	v_lshlrev_b32_e32 v152, 16, v196
	v_and_b32_e32 v153, 0xffff0000, v196
	v_pk_mul_f32 v[126:127], v[126:127], v[152:153]
	v_lshlrev_b32_e32 v152, 16, v197
	v_and_b32_e32 v153, 0xffff0000, v197
	v_pk_mul_f32 v[128:129], v[128:129], v[152:153]
	v_lshlrev_b32_e32 v152, 16, v198
	v_and_b32_e32 v153, 0xffff0000, v198
	v_pk_mul_f32 v[122:123], v[122:123], v[152:153]
	v_lshlrev_b32_e32 v152, 16, v199
	v_and_b32_e32 v153, 0xffff0000, v199
	v_pk_mul_f32 v[124:125], v[124:125], v[152:153]
	s_cmp_lg_u64 s[12:13], 0
	s_cbranch_scc0 .Lepb_na0
	v_lshlrev_b32_e32 v152, 16, v228
	v_and_b32_e32 v153, 0xffff0000, v228
	v_pk_add_f32 v[126:127], v[126:127], v[152:153]
	v_lshlrev_b32_e32 v152, 16, v229
	v_and_b32_e32 v153, 0xffff0000, v229
	v_pk_add_f32 v[128:129], v[128:129], v[152:153]
	v_lshlrev_b32_e32 v152, 16, v230
	v_and_b32_e32 v153, 0xffff0000, v230
	v_pk_add_f32 v[122:123], v[122:123], v[152:153]
	v_lshlrev_b32_e32 v152, 16, v231
	v_and_b32_e32 v153, 0xffff0000, v231
	v_pk_add_f32 v[124:125], v[124:125], v[152:153]
.Lepb_na0:
	v_cvt_pk_bf16_f32 v196, v126, v127
	v_cvt_pk_bf16_f32 v197, v128, v129
	v_cvt_pk_bf16_f32 v198, v122, v123
	v_cvt_pk_bf16_f32 v199, v124, v125
	v_mov_b32_e32 v133, v132
	global_store_dwordx4 v133, v[196:199], s[8:9]
	s_waitcnt vmcnt(7)
	v_lshlrev_b32_e32 v152, 16, v200
	v_and_b32_e32 v153, 0xffff0000, v200
	v_pk_mul_f32 v[118:119], v[118:119], v[152:153]
	v_lshlrev_b32_e32 v152, 16, v201
	v_and_b32_e32 v153, 0xffff0000, v201
	v_pk_mul_f32 v[120:121], v[120:121], v[152:153]
	v_lshlrev_b32_e32 v152, 16, v202
	v_and_b32_e32 v153, 0xffff0000, v202
	v_pk_mul_f32 v[114:115], v[114:115], v[152:153]
	v_lshlrev_b32_e32 v152, 16, v203
	v_and_b32_e32 v153, 0xffff0000, v203
	v_pk_mul_f32 v[116:117], v[116:117], v[152:153]
	s_cmp_lg_u64 s[12:13], 0
	s_cbranch_scc0 .Lepb_na1
	v_lshlrev_b32_e32 v152, 16, v232
	v_and_b32_e32 v153, 0xffff0000, v232
	v_pk_add_f32 v[118:119], v[118:119], v[152:153]
	v_lshlrev_b32_e32 v152, 16, v233
	v_and_b32_e32 v153, 0xffff0000, v233
	v_pk_add_f32 v[120:121], v[120:121], v[152:153]
	v_lshlrev_b32_e32 v152, 16, v234
	v_and_b32_e32 v153, 0xffff0000, v234
	v_pk_add_f32 v[114:115], v[114:115], v[152:153]
	v_lshlrev_b32_e32 v152, 16, v235
	v_and_b32_e32 v153, 0xffff0000, v235
	v_pk_add_f32 v[116:117], v[116:117], v[152:153]
.Lepb_na1:
	v_cvt_pk_bf16_f32 v200, v118, v119
	v_cvt_pk_bf16_f32 v201, v120, v121
	v_cvt_pk_bf16_f32 v202, v114, v115
	v_cvt_pk_bf16_f32 v203, v116, v117
	v_mov_b32_e32 v133, v132
	global_store_dwordx4 v133, v[200:203], s[8:9] offset:256
	s_waitcnt vmcnt(7)
	v_lshlrev_b32_e32 v152, 16, v204
	v_and_b32_e32 v153, 0xffff0000, v204
	v_pk_mul_f32 v[110:111], v[110:111], v[152:153]
	v_lshlrev_b32_e32 v152, 16, v205
	v_and_b32_e32 v153, 0xffff0000, v205
	v_pk_mul_f32 v[112:113], v[112:113], v[152:153]
	v_lshlrev_b32_e32 v152, 16, v206
	v_and_b32_e32 v153, 0xffff0000, v206
	v_pk_mul_f32 v[106:107], v[106:107], v[152:153]
	v_lshlrev_b32_e32 v152, 16, v207
	v_and_b32_e32 v153, 0xffff0000, v207
	v_pk_mul_f32 v[108:109], v[108:109], v[152:153]
	s_cmp_lg_u64 s[12:13], 0
	s_cbranch_scc0 .Lepb_na2
	v_lshlrev_b32_e32 v152, 16, v236
	v_and_b32_e32 v153, 0xffff0000, v236
	v_pk_add_f32 v[110:111], v[110:111], v[152:153]
	v_lshlrev_b32_e32 v152, 16, v237
	v_and_b32_e32 v153, 0xffff0000, v237
	v_pk_add_f32 v[112:113], v[112:113], v[152:153]
	v_lshlrev_b32_e32 v152, 16, v238
	v_and_b32_e32 v153, 0xffff0000, v238
	v_pk_add_f32 v[106:107], v[106:107], v[152:153]
	v_lshlrev_b32_e32 v152, 16, v239
	v_and_b32_e32 v153, 0xffff0000, v239
	v_pk_add_f32 v[108:109], v[108:109], v[152:153]
.Lepb_na2:
	v_cvt_pk_bf16_f32 v204, v110, v111
	v_cvt_pk_bf16_f32 v205, v112, v113
	v_cvt_pk_bf16_f32 v206, v106, v107
	v_cvt_pk_bf16_f32 v207, v108, v109
	v_add_u32_e32 v133, 0x10000, v132
	global_store_dwordx4 v133, v[204:207], s[8:9]
	s_waitcnt vmcnt(7)
	v_lshlrev_b32_e32 v152, 16, v208
	v_and_b32_e32 v153, 0xffff0000, v208
	v_pk_mul_f32 v[102:103], v[102:103], v[152:153]
	v_lshlrev_b32_e32 v152, 16, v209
	v_and_b32_e32 v153, 0xffff0000, v209
	v_pk_mul_f32 v[104:105], v[104:105], v[152:153]
	v_lshlrev_b32_e32 v152, 16, v210
	v_and_b32_e32 v153, 0xffff0000, v210
	v_pk_mul_f32 v[98:99], v[98:99], v[152:153]
	v_lshlrev_b32_e32 v152, 16, v211
	v_and_b32_e32 v153, 0xffff0000, v211
	v_pk_mul_f32 v[100:101], v[100:101], v[152:153]
	s_cmp_lg_u64 s[12:13], 0
	s_cbranch_scc0 .Lepb_na3
	v_lshlrev_b32_e32 v152, 16, v240
	v_and_b32_e32 v153, 0xffff0000, v240
	v_pk_add_f32 v[102:103], v[102:103], v[152:153]
	v_lshlrev_b32_e32 v152, 16, v241
	v_and_b32_e32 v153, 0xffff0000, v241
	v_pk_add_f32 v[104:105], v[104:105], v[152:153]
	v_lshlrev_b32_e32 v152, 16, v242
	v_and_b32_e32 v153, 0xffff0000, v242
	v_pk_add_f32 v[98:99], v[98:99], v[152:153]
	v_lshlrev_b32_e32 v152, 16, v243
	v_and_b32_e32 v153, 0xffff0000, v243
	v_pk_add_f32 v[100:101], v[100:101], v[152:153]
.Lepb_na3:
	v_cvt_pk_bf16_f32 v208, v102, v103
	v_cvt_pk_bf16_f32 v209, v104, v105
	v_cvt_pk_bf16_f32 v210, v98, v99
	v_cvt_pk_bf16_f32 v211, v100, v101
	v_add_u32_e32 v133, 0x10000, v132
	global_store_dwordx4 v133, v[208:211], s[8:9] offset:256
	s_waitcnt vmcnt(7)
	v_lshlrev_b32_e32 v152, 16, v212
	v_and_b32_e32 v153, 0xffff0000, v212
	v_pk_mul_f32 v[94:95], v[94:95], v[152:153]
	v_lshlrev_b32_e32 v152, 16, v213
	v_and_b32_e32 v153, 0xffff0000, v213
	v_pk_mul_f32 v[96:97], v[96:97], v[152:153]
	v_lshlrev_b32_e32 v152, 16, v214
	v_and_b32_e32 v153, 0xffff0000, v214
	v_pk_mul_f32 v[90:91], v[90:91], v[152:153]
	v_lshlrev_b32_e32 v152, 16, v215
	v_and_b32_e32 v153, 0xffff0000, v215
	v_pk_mul_f32 v[92:93], v[92:93], v[152:153]
	s_cmp_lg_u64 s[12:13], 0
	s_cbranch_scc0 .Lepb_na4
	v_lshlrev_b32_e32 v152, 16, v244
	v_and_b32_e32 v153, 0xffff0000, v244
	v_pk_add_f32 v[94:95], v[94:95], v[152:153]
	v_lshlrev_b32_e32 v152, 16, v245
	v_and_b32_e32 v153, 0xffff0000, v245
	v_pk_add_f32 v[96:97], v[96:97], v[152:153]
	v_lshlrev_b32_e32 v152, 16, v246
	v_and_b32_e32 v153, 0xffff0000, v246
	v_pk_add_f32 v[90:91], v[90:91], v[152:153]
	v_lshlrev_b32_e32 v152, 16, v247
	v_and_b32_e32 v153, 0xffff0000, v247
	v_pk_add_f32 v[92:93], v[92:93], v[152:153]
.Lepb_na4:
	v_cvt_pk_bf16_f32 v212, v94, v95
	v_cvt_pk_bf16_f32 v213, v96, v97
	v_cvt_pk_bf16_f32 v214, v90, v91
	v_cvt_pk_bf16_f32 v215, v92, v93
	v_add_u32_e32 v133, 0x20000, v132
	global_store_dwordx4 v133, v[212:215], s[8:9]
	s_waitcnt vmcnt(7)
	v_lshlrev_b32_e32 v152, 16, v216
	v_and_b32_e32 v153, 0xffff0000, v216
	v_pk_mul_f32 v[86:87], v[86:87], v[152:153]
	v_lshlrev_b32_e32 v152, 16, v217
	v_and_b32_e32 v153, 0xffff0000, v217
	v_pk_mul_f32 v[88:89], v[88:89], v[152:153]
	v_lshlrev_b32_e32 v152, 16, v218
	v_and_b32_e32 v153, 0xffff0000, v218
	v_pk_mul_f32 v[82:83], v[82:83], v[152:153]
	v_lshlrev_b32_e32 v152, 16, v219
	v_and_b32_e32 v153, 0xffff0000, v219
	v_pk_mul_f32 v[84:85], v[84:85], v[152:153]
	s_cmp_lg_u64 s[12:13], 0
	s_cbranch_scc0 .Lepb_na5
	v_lshlrev_b32_e32 v152, 16, v176
	v_and_b32_e32 v153, 0xffff0000, v176
	v_pk_add_f32 v[86:87], v[86:87], v[152:153]
	v_lshlrev_b32_e32 v152, 16, v177
	v_and_b32_e32 v153, 0xffff0000, v177
	v_pk_add_f32 v[88:89], v[88:89], v[152:153]
	v_lshlrev_b32_e32 v152, 16, v178
	v_and_b32_e32 v153, 0xffff0000, v178
	v_pk_add_f32 v[82:83], v[82:83], v[152:153]
	v_lshlrev_b32_e32 v152, 16, v179
	v_and_b32_e32 v153, 0xffff0000, v179
	v_pk_add_f32 v[84:85], v[84:85], v[152:153]
.Lepb_na5:
	v_cvt_pk_bf16_f32 v216, v86, v87
	v_cvt_pk_bf16_f32 v217, v88, v89
	v_cvt_pk_bf16_f32 v218, v82, v83
	v_cvt_pk_bf16_f32 v219, v84, v85
	v_add_u32_e32 v133, 0x20000, v132
	global_store_dwordx4 v133, v[216:219], s[8:9] offset:256
	s_waitcnt vmcnt(7)
	v_lshlrev_b32_e32 v152, 16, v220
	v_and_b32_e32 v153, 0xffff0000, v220
	v_pk_mul_f32 v[78:79], v[78:79], v[152:153]
	v_lshlrev_b32_e32 v152, 16, v221
	v_and_b32_e32 v153, 0xffff0000, v221
	v_pk_mul_f32 v[80:81], v[80:81], v[152:153]
	v_lshlrev_b32_e32 v152, 16, v222
	v_and_b32_e32 v153, 0xffff0000, v222
	v_pk_mul_f32 v[74:75], v[74:75], v[152:153]
	v_lshlrev_b32_e32 v152, 16, v223
	v_and_b32_e32 v153, 0xffff0000, v223
	v_pk_mul_f32 v[76:77], v[76:77], v[152:153]
	s_cmp_lg_u64 s[12:13], 0
	s_cbranch_scc0 .Lepb_na6
	v_lshlrev_b32_e32 v152, 16, v134
	v_and_b32_e32 v153, 0xffff0000, v134
	v_pk_add_f32 v[78:79], v[78:79], v[152:153]
	v_lshlrev_b32_e32 v152, 16, v135
	v_and_b32_e32 v153, 0xffff0000, v135
	v_pk_add_f32 v[80:81], v[80:81], v[152:153]
	v_lshlrev_b32_e32 v152, 16, v136
	v_and_b32_e32 v153, 0xffff0000, v136
	v_pk_add_f32 v[74:75], v[74:75], v[152:153]
	v_lshlrev_b32_e32 v152, 16, v137
	v_and_b32_e32 v153, 0xffff0000, v137
	v_pk_add_f32 v[76:77], v[76:77], v[152:153]
.Lepb_na6:
	v_cvt_pk_bf16_f32 v220, v78, v79
	v_cvt_pk_bf16_f32 v221, v80, v81
	v_cvt_pk_bf16_f32 v222, v74, v75
	v_cvt_pk_bf16_f32 v223, v76, v77
	v_add_u32_e32 v133, 0x30000, v132
	global_store_dwordx4 v133, v[220:223], s[8:9]
	s_waitcnt vmcnt(7)
	v_lshlrev_b32_e32 v152, 16, v224
	v_and_b32_e32 v153, 0xffff0000, v224
	v_pk_mul_f32 v[70:71], v[70:71], v[152:153]
	v_lshlrev_b32_e32 v152, 16, v225
	v_and_b32_e32 v153, 0xffff0000, v225
	v_pk_mul_f32 v[72:73], v[72:73], v[152:153]
	v_lshlrev_b32_e32 v152, 16, v226
	v_and_b32_e32 v153, 0xffff0000, v226
	v_pk_mul_f32 v[66:67], v[66:67], v[152:153]
	v_lshlrev_b32_e32 v152, 16, v227
	v_and_b32_e32 v153, 0xffff0000, v227
	v_pk_mul_f32 v[68:69], v[68:69], v[152:153]
	s_cmp_lg_u64 s[12:13], 0
	s_cbranch_scc0 .Lepb_na7
	v_lshlrev_b32_e32 v152, 16, v138
	v_and_b32_e32 v153, 0xffff0000, v138
	v_pk_add_f32 v[70:71], v[70:71], v[152:153]
	v_lshlrev_b32_e32 v152, 16, v139
	v_and_b32_e32 v153, 0xffff0000, v139
	v_pk_add_f32 v[72:73], v[72:73], v[152:153]
	v_lshlrev_b32_e32 v152, 16, v140
	v_and_b32_e32 v153, 0xffff0000, v140
	v_pk_add_f32 v[66:67], v[66:67], v[152:153]
	v_lshlrev_b32_e32 v152, 16, v141
	v_and_b32_e32 v153, 0xffff0000, v141
	v_pk_add_f32 v[68:69], v[68:69], v[152:153]
.Lepb_na7:
	v_cvt_pk_bf16_f32 v224, v70, v71
	v_cvt_pk_bf16_f32 v225, v72, v73
	v_cvt_pk_bf16_f32 v226, v66, v67
	v_cvt_pk_bf16_f32 v227, v68, v69
	v_add_u32_e32 v133, 0x30000, v132
	global_store_dwordx4 v133, v[224:227], s[8:9] offset:256
	v_add_u32_e32 v133, 0x80000, v132
	global_load_dwordx4 v[196:199], v133, s[4:5]
	global_load_dwordx4 v[200:203], v133, s[4:5] offset:256
	v_add_u32_e32 v133, 0x90000, v132
	global_load_dwordx4 v[204:207], v133, s[4:5]
	global_load_dwordx4 v[208:211], v133, s[4:5] offset:256
	v_add_u32_e32 v133, 0xa0000, v132
	global_load_dwordx4 v[212:215], v133, s[4:5]
	global_load_dwordx4 v[216:219], v133, s[4:5] offset:256
	v_add_u32_e32 v133, 0xb0000, v132
	global_load_dwordx4 v[220:223], v133, s[4:5]
	global_load_dwordx4 v[224:227], v133, s[4:5] offset:256
	s_cmp_lg_u64 s[12:13], 0
	s_cbranch_scc0 .Lepb_nom1
	v_add_u32_e32 v133, 0x80000, v132
	global_load_dwordx4 v[228:231], v133, s[64:65]
	global_load_dwordx4 v[232:235], v133, s[64:65] offset:256
	v_add_u32_e32 v133, 0x90000, v132
	global_load_dwordx4 v[236:239], v133, s[64:65]
	global_load_dwordx4 v[240:243], v133, s[64:65] offset:256
	v_add_u32_e32 v133, 0xa0000, v132
	global_load_dwordx4 v[244:247], v133, s[64:65]
	global_load_dwordx4 v[176:179], v133, s[64:65] offset:256
	v_add_u32_e32 v133, 0xb0000, v132
	global_load_dwordx4 v[134:137], v133, s[64:65]
	global_load_dwordx4 v[138:141], v133, s[64:65] offset:256
.Lepb_nom1:
	s_waitcnt vmcnt(7)
	v_lshlrev_b32_e32 v152, 16, v196
	v_and_b32_e32 v153, 0xffff0000, v196
	v_pk_mul_f32 v[60:61], v[60:61], v[152:153]
	v_lshlrev_b32_e32 v152, 16, v197
	v_and_b32_e32 v153, 0xffff0000, v197
	v_pk_mul_f32 v[62:63], v[62:63], v[152:153]
	v_lshlrev_b32_e32 v152, 16, v198
	v_and_b32_e32 v153, 0xffff0000, v198
	v_pk_mul_f32 v[56:57], v[56:57], v[152:153]
	v_lshlrev_b32_e32 v152, 16, v199
	v_and_b32_e32 v153, 0xffff0000, v199
	v_pk_mul_f32 v[58:59], v[58:59], v[152:153]
	s_cmp_lg_u64 s[12:13], 0
	s_cbranch_scc0 .Lepb_na8
	v_lshlrev_b32_e32 v152, 16, v228
	v_and_b32_e32 v153, 0xffff0000, v228
	v_pk_add_f32 v[60:61], v[60:61], v[152:153]
	v_lshlrev_b32_e32 v152, 16, v229
	v_and_b32_e32 v153, 0xffff0000, v229
	v_pk_add_f32 v[62:63], v[62:63], v[152:153]
	v_lshlrev_b32_e32 v152, 16, v230
	v_and_b32_e32 v153, 0xffff0000, v230
	v_pk_add_f32 v[56:57], v[56:57], v[152:153]
	v_lshlrev_b32_e32 v152, 16, v231
	v_and_b32_e32 v153, 0xffff0000, v231
	v_pk_add_f32 v[58:59], v[58:59], v[152:153]
.Lepb_na8:
	v_cvt_pk_bf16_f32 v196, v60, v61
	v_cvt_pk_bf16_f32 v197, v62, v63
	v_cvt_pk_bf16_f32 v198, v56, v57
	v_cvt_pk_bf16_f32 v199, v58, v59
	v_add_u32_e32 v133, 0x80000, v132
	global_store_dwordx4 v133, v[196:199], s[8:9]
	s_waitcnt vmcnt(7)
	v_lshlrev_b32_e32 v152, 16, v200
	v_and_b32_e32 v153, 0xffff0000, v200
	v_pk_mul_f32 v[52:53], v[52:53], v[152:153]
	v_lshlrev_b32_e32 v152, 16, v201
	v_and_b32_e32 v153, 0xffff0000, v201
	v_pk_mul_f32 v[54:55], v[54:55], v[152:153]
	v_lshlrev_b32_e32 v152, 16, v202
	v_and_b32_e32 v153, 0xffff0000, v202
	v_pk_mul_f32 v[48:49], v[48:49], v[152:153]
	v_lshlrev_b32_e32 v152, 16, v203
	v_and_b32_e32 v153, 0xffff0000, v203
	v_pk_mul_f32 v[50:51], v[50:51], v[152:153]
	s_cmp_lg_u64 s[12:13], 0
	s_cbranch_scc0 .Lepb_na9
	v_lshlrev_b32_e32 v152, 16, v232
	v_and_b32_e32 v153, 0xffff0000, v232
	v_pk_add_f32 v[52:53], v[52:53], v[152:153]
	v_lshlrev_b32_e32 v152, 16, v233
	v_and_b32_e32 v153, 0xffff0000, v233
	v_pk_add_f32 v[54:55], v[54:55], v[152:153]
	v_lshlrev_b32_e32 v152, 16, v234
	v_and_b32_e32 v153, 0xffff0000, v234
	v_pk_add_f32 v[48:49], v[48:49], v[152:153]
	v_lshlrev_b32_e32 v152, 16, v235
	v_and_b32_e32 v153, 0xffff0000, v235
	v_pk_add_f32 v[50:51], v[50:51], v[152:153]
.Lepb_na9:
	v_cvt_pk_bf16_f32 v200, v52, v53
	v_cvt_pk_bf16_f32 v201, v54, v55
	v_cvt_pk_bf16_f32 v202, v48, v49
	v_cvt_pk_bf16_f32 v203, v50, v51
	v_add_u32_e32 v133, 0x80000, v132
	global_store_dwordx4 v133, v[200:203], s[8:9] offset:256
	s_waitcnt vmcnt(7)
	v_lshlrev_b32_e32 v152, 16, v204
	v_and_b32_e32 v153, 0xffff0000, v204
	v_pk_mul_f32 v[44:45], v[44:45], v[152:153]
	v_lshlrev_b32_e32 v152, 16, v205
	v_and_b32_e32 v153, 0xffff0000, v205
	v_pk_mul_f32 v[46:47], v[46:47], v[152:153]
	v_lshlrev_b32_e32 v152, 16, v206
	v_and_b32_e32 v153, 0xffff0000, v206
	v_pk_mul_f32 v[40:41], v[40:41], v[152:153]
	v_lshlrev_b32_e32 v152, 16, v207
	v_and_b32_e32 v153, 0xffff0000, v207
	v_pk_mul_f32 v[42:43], v[42:43], v[152:153]
	s_cmp_lg_u64 s[12:13], 0
	s_cbranch_scc0 .Lepb_na10
	v_lshlrev_b32_e32 v152, 16, v236
	v_and_b32_e32 v153, 0xffff0000, v236
	v_pk_add_f32 v[44:45], v[44:45], v[152:153]
	v_lshlrev_b32_e32 v152, 16, v237
	v_and_b32_e32 v153, 0xffff0000, v237
	v_pk_add_f32 v[46:47], v[46:47], v[152:153]
	v_lshlrev_b32_e32 v152, 16, v238
	v_and_b32_e32 v153, 0xffff0000, v238
	v_pk_add_f32 v[40:41], v[40:41], v[152:153]
	v_lshlrev_b32_e32 v152, 16, v239
	v_and_b32_e32 v153, 0xffff0000, v239
	v_pk_add_f32 v[42:43], v[42:43], v[152:153]
.Lepb_na10:
	v_cvt_pk_bf16_f32 v204, v44, v45
	v_cvt_pk_bf16_f32 v205, v46, v47
	v_cvt_pk_bf16_f32 v206, v40, v41
	v_cvt_pk_bf16_f32 v207, v42, v43
	v_add_u32_e32 v133, 0x90000, v132
	global_store_dwordx4 v133, v[204:207], s[8:9]
	s_waitcnt vmcnt(7)
	v_lshlrev_b32_e32 v152, 16, v208
	v_and_b32_e32 v153, 0xffff0000, v208
	v_pk_mul_f32 v[36:37], v[36:37], v[152:153]
	v_lshlrev_b32_e32 v152, 16, v209
	v_and_b32_e32 v153, 0xffff0000, v209
	v_pk_mul_f32 v[38:39], v[38:39], v[152:153]
	v_lshlrev_b32_e32 v152, 16, v210
	v_and_b32_e32 v153, 0xffff0000, v210
	v_pk_mul_f32 v[32:33], v[32:33], v[152:153]
	v_lshlrev_b32_e32 v152, 16, v211
	v_and_b32_e32 v153, 0xffff0000, v211
	v_pk_mul_f32 v[34:35], v[34:35], v[152:153]
	s_cmp_lg_u64 s[12:13], 0
	s_cbranch_scc0 .Lepb_na11
	v_lshlrev_b32_e32 v152, 16, v240
	v_and_b32_e32 v153, 0xffff0000, v240
	v_pk_add_f32 v[36:37], v[36:37], v[152:153]
	v_lshlrev_b32_e32 v152, 16, v241
	v_and_b32_e32 v153, 0xffff0000, v241
	v_pk_add_f32 v[38:39], v[38:39], v[152:153]
	v_lshlrev_b32_e32 v152, 16, v242
	v_and_b32_e32 v153, 0xffff0000, v242
	v_pk_add_f32 v[32:33], v[32:33], v[152:153]
	v_lshlrev_b32_e32 v152, 16, v243
	v_and_b32_e32 v153, 0xffff0000, v243
	v_pk_add_f32 v[34:35], v[34:35], v[152:153]
.Lepb_na11:
	v_cvt_pk_bf16_f32 v208, v36, v37
	v_cvt_pk_bf16_f32 v209, v38, v39
	v_cvt_pk_bf16_f32 v210, v32, v33
	v_cvt_pk_bf16_f32 v211, v34, v35
	v_add_u32_e32 v133, 0x90000, v132
	global_store_dwordx4 v133, v[208:211], s[8:9] offset:256
	s_waitcnt vmcnt(7)
	v_lshlrev_b32_e32 v152, 16, v212
	v_and_b32_e32 v153, 0xffff0000, v212
	v_pk_mul_f32 v[28:29], v[28:29], v[152:153]
	v_lshlrev_b32_e32 v152, 16, v213
	v_and_b32_e32 v153, 0xffff0000, v213
	v_pk_mul_f32 v[30:31], v[30:31], v[152:153]
	v_lshlrev_b32_e32 v152, 16, v214
	v_and_b32_e32 v153, 0xffff0000, v214
	v_pk_mul_f32 v[24:25], v[24:25], v[152:153]
	v_lshlrev_b32_e32 v152, 16, v215
	v_and_b32_e32 v153, 0xffff0000, v215
	v_pk_mul_f32 v[26:27], v[26:27], v[152:153]
	s_cmp_lg_u64 s[12:13], 0
	s_cbranch_scc0 .Lepb_na12
	v_lshlrev_b32_e32 v152, 16, v244
	v_and_b32_e32 v153, 0xffff0000, v244
	v_pk_add_f32 v[28:29], v[28:29], v[152:153]
	v_lshlrev_b32_e32 v152, 16, v245
	v_and_b32_e32 v153, 0xffff0000, v245
	v_pk_add_f32 v[30:31], v[30:31], v[152:153]
	v_lshlrev_b32_e32 v152, 16, v246
	v_and_b32_e32 v153, 0xffff0000, v246
	v_pk_add_f32 v[24:25], v[24:25], v[152:153]
	v_lshlrev_b32_e32 v152, 16, v247
	v_and_b32_e32 v153, 0xffff0000, v247
	v_pk_add_f32 v[26:27], v[26:27], v[152:153]
.Lepb_na12:
	v_cvt_pk_bf16_f32 v212, v28, v29
	v_cvt_pk_bf16_f32 v213, v30, v31
	v_cvt_pk_bf16_f32 v214, v24, v25
	v_cvt_pk_bf16_f32 v215, v26, v27
	v_add_u32_e32 v133, 0xa0000, v132
	global_store_dwordx4 v133, v[212:215], s[8:9]
	s_waitcnt vmcnt(7)
	v_lshlrev_b32_e32 v152, 16, v216
	v_and_b32_e32 v153, 0xffff0000, v216
	v_pk_mul_f32 v[20:21], v[20:21], v[152:153]
	v_lshlrev_b32_e32 v152, 16, v217
	v_and_b32_e32 v153, 0xffff0000, v217
	v_pk_mul_f32 v[22:23], v[22:23], v[152:153]
	v_lshlrev_b32_e32 v152, 16, v218
	v_and_b32_e32 v153, 0xffff0000, v218
	v_pk_mul_f32 v[16:17], v[16:17], v[152:153]
	v_lshlrev_b32_e32 v152, 16, v219
	v_and_b32_e32 v153, 0xffff0000, v219
	v_pk_mul_f32 v[18:19], v[18:19], v[152:153]
	s_cmp_lg_u64 s[12:13], 0
	s_cbranch_scc0 .Lepb_na13
	v_lshlrev_b32_e32 v152, 16, v176
	v_and_b32_e32 v153, 0xffff0000, v176
	v_pk_add_f32 v[20:21], v[20:21], v[152:153]
	v_lshlrev_b32_e32 v152, 16, v177
	v_and_b32_e32 v153, 0xffff0000, v177
	v_pk_add_f32 v[22:23], v[22:23], v[152:153]
	v_lshlrev_b32_e32 v152, 16, v178
	v_and_b32_e32 v153, 0xffff0000, v178
	v_pk_add_f32 v[16:17], v[16:17], v[152:153]
	v_lshlrev_b32_e32 v152, 16, v179
	v_and_b32_e32 v153, 0xffff0000, v179
	v_pk_add_f32 v[18:19], v[18:19], v[152:153]
.Lepb_na13:
	v_cvt_pk_bf16_f32 v216, v20, v21
	v_cvt_pk_bf16_f32 v217, v22, v23
	v_cvt_pk_bf16_f32 v218, v16, v17
	v_cvt_pk_bf16_f32 v219, v18, v19
	v_add_u32_e32 v133, 0xa0000, v132
	global_store_dwordx4 v133, v[216:219], s[8:9] offset:256
	s_waitcnt vmcnt(7)
	v_lshlrev_b32_e32 v152, 16, v220
	v_and_b32_e32 v153, 0xffff0000, v220
	v_pk_mul_f32 v[12:13], v[12:13], v[152:153]
	v_lshlrev_b32_e32 v152, 16, v221
	v_and_b32_e32 v153, 0xffff0000, v221
	v_pk_mul_f32 v[14:15], v[14:15], v[152:153]
	v_lshlrev_b32_e32 v152, 16, v222
	v_and_b32_e32 v153, 0xffff0000, v222
	v_pk_mul_f32 v[8:9], v[8:9], v[152:153]
	v_lshlrev_b32_e32 v152, 16, v223
	v_and_b32_e32 v153, 0xffff0000, v223
	v_pk_mul_f32 v[10:11], v[10:11], v[152:153]
	s_cmp_lg_u64 s[12:13], 0
	s_cbranch_scc0 .Lepb_na14
	v_lshlrev_b32_e32 v152, 16, v134
	v_and_b32_e32 v153, 0xffff0000, v134
	v_pk_add_f32 v[12:13], v[12:13], v[152:153]
	v_lshlrev_b32_e32 v152, 16, v135
	v_and_b32_e32 v153, 0xffff0000, v135
	v_pk_add_f32 v[14:15], v[14:15], v[152:153]
	v_lshlrev_b32_e32 v152, 16, v136
	v_and_b32_e32 v153, 0xffff0000, v136
	v_pk_add_f32 v[8:9], v[8:9], v[152:153]
	v_lshlrev_b32_e32 v152, 16, v137
	v_and_b32_e32 v153, 0xffff0000, v137
	v_pk_add_f32 v[10:11], v[10:11], v[152:153]
.Lepb_na14:
	v_cvt_pk_bf16_f32 v220, v12, v13
	v_cvt_pk_bf16_f32 v221, v14, v15
	v_cvt_pk_bf16_f32 v222, v8, v9
	v_cvt_pk_bf16_f32 v223, v10, v11
	v_add_u32_e32 v133, 0xb0000, v132
	global_store_dwordx4 v133, v[220:223], s[8:9]
	s_waitcnt vmcnt(7)
	v_lshlrev_b32_e32 v152, 16, v224
	v_and_b32_e32 v153, 0xffff0000, v224
	v_pk_mul_f32 v[4:5], v[4:5], v[152:153]
	v_lshlrev_b32_e32 v152, 16, v225
	v_and_b32_e32 v153, 0xffff0000, v225
	v_pk_mul_f32 v[6:7], v[6:7], v[152:153]
	v_lshlrev_b32_e32 v152, 16, v226
	v_and_b32_e32 v153, 0xffff0000, v226
	v_pk_mul_f32 v[0:1], v[0:1], v[152:153]
	v_lshlrev_b32_e32 v152, 16, v227
	v_and_b32_e32 v153, 0xffff0000, v227
	v_pk_mul_f32 v[2:3], v[2:3], v[152:153]
	s_cmp_lg_u64 s[12:13], 0
	s_cbranch_scc0 .Lepb_na15
	v_lshlrev_b32_e32 v152, 16, v138
	v_and_b32_e32 v153, 0xffff0000, v138
	v_pk_add_f32 v[4:5], v[4:5], v[152:153]
	v_lshlrev_b32_e32 v152, 16, v139
	v_and_b32_e32 v153, 0xffff0000, v139
	v_pk_add_f32 v[6:7], v[6:7], v[152:153]
	v_lshlrev_b32_e32 v152, 16, v140
	v_and_b32_e32 v153, 0xffff0000, v140
	v_pk_add_f32 v[0:1], v[0:1], v[152:153]
	v_lshlrev_b32_e32 v152, 16, v141
	v_and_b32_e32 v153, 0xffff0000, v141
	v_pk_add_f32 v[2:3], v[2:3], v[152:153]
.Lepb_na15:
	v_cvt_pk_bf16_f32 v224, v4, v5
	v_cvt_pk_bf16_f32 v225, v6, v7
	v_cvt_pk_bf16_f32 v226, v0, v1
	v_cvt_pk_bf16_f32 v227, v2, v3
	v_add_u32_e32 v133, 0xb0000, v132
	global_store_dwordx4 v133, v[224:227], s[8:9] offset:256
	s_andn2_b64 vcc, exec, s[62:63]
	s_mov_b64 s[16:17], -1
	s_cbranch_vccnz .LBB0_181
	s_andn2_b64 vcc, exec, s[6:7]
	s_cbranch_vccnz .LBB0_180
	s_barrier
	s_branch .LBB0_180
